# attention phase: gain loads preloaded, V-row wait moved to first consumer, spurious vmcnt waits between K-row loads removed
# speedup vs baseline: 1.0020x; 1.0020x over previous
.LBB0_690:
	s_waitcnt lgkmcnt(0)
	v_add_f32_e32 v1, v247, v248
	v_div_scale_f32 v2, s[4:5], v1, v1, 1.0
	v_rcp_f32_e32 v3, v2
	v_div_scale_f32 v172, vcc, 1.0, v1, 1.0
	s_add_i32 s4, s78, s60
	v_fma_f32 v173, -v2, v3, 1.0
	v_fmac_f32_e32 v3, v173, v3
	v_mul_f32_e32 v173, v172, v3
	v_fma_f32 v174, -v2, v173, v172
	v_fmac_f32_e32 v173, v174, v3
	v_fma_f32 v2, -v2, v173, v172
	v_div_fmas_f32 v2, v2, v3, v173
	v_div_fixup_f32 v2, v2, v1, 1.0
	v_pk_mul_f32 v[164:165], v[2:3], v[164:165] op_sel_hi:[0,1]
	v_pk_mul_f32 v[168:169], v[2:3], v[168:169] op_sel_hi:[0,1]
	v_pk_mul_f32 v[166:167], v[2:3], v[166:167] op_sel_hi:[0,1]
	v_pk_mul_f32 v[170:171], v[2:3], v[170:171] op_sel_hi:[0,1]
	v_mov_b32_e32 v174, v165
	v_mov_b32_e32 v175, v169
	v_mov_b32_e32 v172, v164
	v_mov_b32_e32 v173, v168
	v_pk_mul_f32 v[174:175], v[174:175], v[174:175]
	v_mov_b32_e32 v176, v167
	v_mov_b32_e32 v177, v171
	v_pk_fma_f32 v[172:173], v[172:173], v[172:173], v[174:175]
	v_mov_b32_e32 v174, v166
	v_mov_b32_e32 v175, v170
	v_pk_mul_f32 v[176:177], v[176:177], v[176:177]
	s_lshl_b32 s76, s61, 1
	v_pk_fma_f32 v[174:175], v[174:175], v[174:175], v[176:177]
	v_pk_mul_f32 v[176:177], v[2:3], v[162:163] op_sel_hi:[0,1]
	v_pk_add_f32 v[172:173], v[172:173], v[174:175]
	v_pk_mul_f32 v[174:175], v[2:3], v[160:161] op_sel_hi:[0,1]
	v_or_b32_e32 v160, s4, v224
	v_ashrrev_i32_e32 v161, 31, v160
	v_lshlrev_b64 v[160:161], 12, v[160:161]
	v_lshl_add_u64 v[160:161], s[74:75], 0, v[160:161]
	v_lshl_add_u64 v[180:181], v[160:161], 0, s[76:77]
	s_lshl_b32 s76, s61, 2
	v_lshl_add_u64 v[182:183], v[232:233], 0, s[76:77]
	global_load_dwordx4 v[160:163], v[182:183], off
	global_load_dwordx4 v[4:7], v[182:183], off offset:64
	global_load_dwordx4 v[8:11], v[182:183], off offset:128
	global_load_dwordx4 v[12:15], v[182:183], off offset:192
	global_load_dwordx4 v[16:19], v[182:183], off offset:256
	global_load_dwordx4 v[20:23], v[182:183], off offset:320
	global_load_dwordx4 v[24:27], v[182:183], off offset:384
	global_load_dwordx4 v[28:31], v[182:183], off offset:448
	v_pk_mul_f32 v[178:179], v[176:177], v[176:177]
	v_pk_mul_f32 v[184:185], v[174:175], v[174:175]
	v_pk_mul_f32 v[156:157], v[2:3], v[156:157] op_sel_hi:[0,1]
	v_pk_mov_b32 v[186:187], v[184:185], v[178:179] op_sel:[1,0]
	v_mov_b32_e32 v185, v179
	v_pk_add_f32 v[178:179], v[186:187], v[184:185]
	v_pk_mul_f32 v[150:151], v[2:3], v[150:151] op_sel_hi:[0,1]
	v_pk_mul_f32 v[148:149], v[2:3], v[148:149] op_sel_hi:[0,1]
	v_pk_mul_f32 v[158:159], v[2:3], v[158:159] op_sel_hi:[0,1]
	v_mul_f32_e32 v1, v156, v156
	v_mul_f32_e32 v3, v157, v157
	v_pk_add_f32 v[172:173], v[172:173], v[172:173] op_sel:[0,1] op_sel_hi:[1,0]
	v_pk_add_f32 v[178:179], v[178:179], v[178:179] op_sel:[0,1] op_sel_hi:[1,0]
	v_mov_b32_e32 v173, v1
	v_mov_b32_e32 v179, v3
	v_pk_add_f32 v[172:173], v[172:173], v[178:179]
	v_mul_f32_e32 v178, v149, v149
	v_mul_f32_e32 v184, v158, v158
	v_pk_fma_f32 v[178:179], v[148:149], v[148:149], v[178:179] op_sel_hi:[1,1,0]
	v_mul_f32_e32 v186, v159, v159
	v_mov_b32_e32 v179, v184
	v_mul_f32_e32 v184, v151, v151
	v_pk_fma_f32 v[184:185], v[150:151], v[150:151], v[184:185] op_sel_hi:[1,1,0]
	v_pk_mul_f32 v[146:147], v[2:3], v[146:147] op_sel_hi:[0,1]
	v_mov_b32_e32 v185, v186
	v_pk_add_f32 v[178:179], v[178:179], v[184:185]
	v_pk_mul_f32 v[184:185], v[2:3], v[142:143] op_sel_hi:[0,1]
	v_pk_add_f32 v[172:173], v[172:173], v[178:179]
	v_pk_mul_f32 v[178:179], v[2:3], v[140:141] op_sel_hi:[0,1]
	v_pk_mul_f32 v[140:141], v[184:185], v[184:185]
	v_pk_mul_f32 v[142:143], v[178:179], v[178:179]
	v_pk_mul_f32 v[144:145], v[2:3], v[144:145] op_sel_hi:[0,1]
	v_pk_mov_b32 v[186:187], v[142:143], v[140:141] op_sel:[1,0]
	v_mov_b32_e32 v143, v141
	v_pk_add_f32 v[140:141], v[186:187], v[142:143]
	v_pk_mul_f32 v[154:155], v[2:3], v[154:155] op_sel_hi:[0,1]
	v_pk_mul_f32 v[2:3], v[2:3], v[152:153] op_sel_hi:[0,1]
	v_mul_f32_e32 v1, v2, v2
	v_mul_f32_e32 v152, v3, v3
	v_pk_add_f32 v[142:143], v[172:173], v[172:173] op_sel:[0,1] op_sel_hi:[1,0]
	v_pk_add_f32 v[140:141], v[140:141], v[140:141] op_sel:[0,1] op_sel_hi:[1,0]
	v_mov_b32_e32 v143, v1
	v_mov_b32_e32 v141, v152
	v_pk_add_f32 v[140:141], v[142:143], v[140:141]
	v_mul_f32_e32 v142, v145, v145
	v_mul_f32_e32 v153, v154, v154
	v_pk_fma_f32 v[142:143], v[144:145], v[144:145], v[142:143] op_sel_hi:[1,1,0]
	v_mul_f32_e32 v152, v147, v147
	v_mul_f32_e32 v186, v155, v155
	v_mov_b32_e32 v143, v153
	v_pk_fma_f32 v[152:153], v[146:147], v[146:147], v[152:153] op_sel_hi:[1,1,0]
	v_lshl_add_u64 v[172:173], v[230:231], 1, v[180:181]
	v_mov_b32_e32 v153, v186
	v_pk_add_f32 v[142:143], v[142:143], v[152:153]
	s_add_i32 s97, s97, s46
	v_pk_add_f32 v[140:141], v[140:141], v[142:143]
	s_add_i32 s80, s80, s81
	v_add_f32_e32 v1, v140, v141
	ds_bpermute_b32 v140, v245, v1
	s_cmpk_gt_i32 s97, 0x1ff
	s_waitcnt lgkmcnt(0)
	v_add_f32_e32 v1, v1, v140
	ds_bpermute_b32 v140, v246, v1
	s_waitcnt lgkmcnt(0)
	v_add_f32_e32 v1, v1, v140
	v_fmamk_f32 v1, v1, 0x3c000000, v242
	v_mul_f32_e32 v140, 0x4b800000, v1
	v_cmp_gt_f32_e32 vcc, s96, v1
	s_nop 1
	v_cndmask_b32_e32 v1, v1, v140, vcc
	v_rsq_f32_e32 v1, v1
	s_nop 0
	v_mul_f32_e32 v140, 0x45800000, v1
	v_cndmask_b32_e32 v152, v1, v140, vcc
	v_pk_mul_f32 v[140:141], v[152:153], v[164:165] op_sel_hi:[0,1]
	v_pk_mul_f32 v[142:143], v[152:153], v[166:167] op_sel_hi:[0,1]
	s_waitcnt vmcnt(0)
	v_pk_mul_f32 v[140:141], v[160:161], v[140:141]
	v_pk_mul_f32 v[142:143], v[162:163], v[142:143]
	v_cvt_pk_bf16_f32 v140, v140, v141
	v_pk_mul_f32 v[160:161], v[152:153], v[168:169] op_sel_hi:[0,1]
	v_cvt_pk_bf16_f32 v141, v142, v143
	global_store_dwordx2 v[172:173], v[140:141], off
	v_pk_mul_f32 v[162:163], v[152:153], v[170:171] op_sel_hi:[0,1]
	v_pk_mul_f32 v[148:149], v[152:153], v[148:149] op_sel_hi:[0,1]
	v_pk_mul_f32 v[150:151], v[152:153], v[150:151] op_sel_hi:[0,1]
	v_pk_mul_f32 v[144:145], v[152:153], v[144:145] op_sel_hi:[0,1]
	v_pk_mul_f32 v[146:147], v[152:153], v[146:147] op_sel_hi:[0,1]
	v_pk_mul_f32 v[2:3], v[152:153], v[2:3] op_sel_hi:[0,1]
	v_pk_mul_f32 v[140:141], v[4:5], v[160:161]
	v_pk_mul_f32 v[142:143], v[6:7], v[162:163]
	v_cvt_pk_bf16_f32 v140, v140, v141
	v_pk_mul_f32 v[160:161], v[152:153], v[174:175] op_sel_hi:[0,1]
	v_cvt_pk_bf16_f32 v141, v142, v143
	global_store_dwordx2 v[172:173], v[140:141], off offset:32
	v_pk_mul_f32 v[162:163], v[152:153], v[176:177] op_sel_hi:[0,1]
	v_pk_mul_f32 v[140:141], v[8:9], v[160:161]
	v_pk_mul_f32 v[142:143], v[10:11], v[162:163]
	v_cvt_pk_bf16_f32 v140, v140, v141
	s_nop 0
	v_cvt_pk_bf16_f32 v141, v142, v143
	global_store_dwordx2 v[172:173], v[140:141], off offset:64
	v_pk_mul_f32 v[140:141], v[12:13], v[148:149]
	v_pk_mul_f32 v[142:143], v[14:15], v[150:151]
	v_cvt_pk_bf16_f32 v140, v140, v141
	v_pk_mul_f32 v[148:149], v[152:153], v[156:157] op_sel_hi:[0,1]
	v_cvt_pk_bf16_f32 v141, v142, v143
	global_store_dwordx2 v[172:173], v[140:141], off offset:96
	v_pk_mul_f32 v[150:151], v[152:153], v[158:159] op_sel_hi:[0,1]
	v_pk_mul_f32 v[140:141], v[16:17], v[148:149]
	v_pk_mul_f32 v[142:143], v[18:19], v[150:151]
	v_cvt_pk_bf16_f32 v140, v140, v141
	v_pk_mul_f32 v[148:149], v[152:153], v[178:179] op_sel_hi:[0,1]
	v_cvt_pk_bf16_f32 v141, v142, v143
	global_store_dwordx2 v[172:173], v[140:141], off offset:128
	v_pk_mul_f32 v[150:151], v[152:153], v[184:185] op_sel_hi:[0,1]
	v_pk_mul_f32 v[140:141], v[20:21], v[148:149]
	v_pk_mul_f32 v[142:143], v[22:23], v[150:151]
	v_cvt_pk_bf16_f32 v140, v140, v141
	s_nop 0
	v_cvt_pk_bf16_f32 v141, v142, v143
	global_store_dwordx2 v[172:173], v[140:141], off offset:160
	v_pk_mul_f32 v[140:141], v[24:25], v[144:145]
	v_pk_mul_f32 v[142:143], v[26:27], v[146:147]
	v_cvt_pk_bf16_f32 v140, v140, v141
	v_pk_mul_f32 v[144:145], v[152:153], v[154:155] op_sel_hi:[0,1]
	v_cvt_pk_bf16_f32 v141, v142, v143
	global_store_dwordx2 v[172:173], v[140:141], off offset:192
	v_pk_mul_f32 v[2:3], v[28:29], v[2:3]
	v_pk_mul_f32 v[142:143], v[30:31], v[144:145]
	v_cvt_pk_bf16_f32 v2, v2, v3
	s_nop 0
	v_cvt_pk_bf16_f32 v3, v142, v143
	global_store_dwordx2 v[172:173], v[2:3], off offset:224
	s_cbranch_scc1 .LBB0_867

.LBB0_696:
	s_ashr_i32 s4, s97, 8
	s_and_b32 s5, s80, 14
	s_add_i32 s26, s5, s4
	s_lshr_b32 s4, s97, 2
	s_and_b32 s35, s4, 62
	v_sub_u32_e64 v1, s35, 4 clamp
	s_ashr_i32 s27, s26, 31
	v_readfirstlane_b32 s4, v1
	v_sub_u32_e64 v1, s35, 3 clamp
	s_min_u32 s22, s4, 56
	v_readfirstlane_b32 s4, v1
	s_min_u32 s4, s4, 56
	s_lshl_b64 s[20:21], s[26:27], 12
	s_lshl_b32 s27, s22, 6
	s_sub_i32 s83, s4, s22
	s_or_b32 s4, s20, s27
	s_mov_b32 s5, s21
	s_add_i32 s83, s83, 8
	s_lshl_b64 s[4:5], s[4:5], 8
	s_cmp_gt_i32 s83, 0
	s_cselect_b64 s[18:19], -1, 0
	s_cmp_lt_i32 s83, 1
	v_lshl_add_u64 v[2:3], v[222:223], 0, s[4:5]
	s_cbranch_scc1 .LBB0_698
	v_add_co_u32_e32 v8, vcc, 0x2000, v2
	s_nop 1
	v_addc_co_u32_e32 v9, vcc, 0, v3, vcc
	global_load_dwordx4 v[4:7], v[2:3], off
	s_nop 0
	global_load_dwordx4 v[8:11], v[8:9], off
.LBB0_698:
	s_cmp_gt_i32 s83, 1
	s_cselect_b64 s[4:5], -1, 0
	s_cmp_lt_i32 s83, 2
	s_cbranch_scc1 .LBB0_706
	v_add_co_u32_e32 v12, vcc, 0x4000, v2
	s_nop 1
	v_addc_co_u32_e32 v13, vcc, 0, v3, vcc
	v_add_co_u32_e32 v28, vcc, 0x6000, v2
	s_nop 1
	v_addc_co_u32_e32 v29, vcc, 0, v3, vcc
	global_load_dwordx4 v[12:15], v[12:13], off
	s_nop 0
	global_load_dwordx4 v[28:31], v[28:29], off
	s_cmp_gt_i32 s83, 2
	s_cselect_b64 s[16:17], -1, 0
	s_cmp_lt_i32 s83, 3
	s_cbranch_scc0 .LBB0_707

.LBB0_701:
	v_add_co_u32_e32 v20, vcc, 0xc000, v2
	s_nop 1
	v_addc_co_u32_e32 v21, vcc, 0, v3, vcc
	v_add_co_u32_e32 v44, vcc, 0xe000, v2
	s_nop 1
	v_addc_co_u32_e32 v45, vcc, 0, v3, vcc
	global_load_dwordx4 v[20:23], v[20:21], off
	s_nop 0
	global_load_dwordx4 v[44:47], v[44:45], off
	s_cmp_gt_i32 s83, 4
	s_cselect_b64 s[12:13], -1, 0
	s_cmp_lt_i32 s83, 5
	s_cbranch_scc0 .LBB0_709

.LBB0_703:
	v_add_co_u32_e32 v32, vcc, 0x14000, v2
	s_nop 1
	v_addc_co_u32_e32 v33, vcc, 0, v3, vcc
	v_add_co_u32_e32 v60, vcc, 0x16000, v2
	s_nop 1
	v_addc_co_u32_e32 v61, vcc, 0, v3, vcc
	global_load_dwordx4 v[32:35], v[32:33], off
	s_nop 0
	global_load_dwordx4 v[60:63], v[60:61], off
	s_cmp_gt_i32 s83, 6
	s_cselect_b64 s[8:9], -1, 0
	s_cmp_lt_i32 s83, 7
	s_cbranch_scc0 .LBB0_711

.LBB0_705:
	v_add_co_u32_e32 v48, vcc, 0x1c000, v2
	s_nop 1
	v_addc_co_u32_e32 v49, vcc, 0, v3, vcc
	v_add_co_u32_e32 v68, vcc, 0x1e000, v2
	s_nop 1
	v_addc_co_u32_e32 v69, vcc, 0, v3, vcc
	global_load_dwordx4 v[48:51], v[48:49], off
	s_nop 0
	global_load_dwordx4 v[68:71], v[68:69], off
	s_cmp_gt_i32 s83, 8
	s_cselect_b64 s[28:29], -1, 0
	s_cmp_lt_i32 s83, 9
	s_cbranch_scc0 .LBB0_713
	s_branch .LBB0_714

.LBB0_707:
	v_add_co_u32_e32 v16, vcc, 0x8000, v2
	s_nop 1
	v_addc_co_u32_e32 v17, vcc, 0, v3, vcc
	v_add_co_u32_e32 v36, vcc, 0xa000, v2
	s_nop 1
	v_addc_co_u32_e32 v37, vcc, 0, v3, vcc
	global_load_dwordx4 v[16:19], v[16:17], off
	s_nop 0
	global_load_dwordx4 v[36:39], v[36:37], off
	s_cmp_gt_i32 s83, 3
	s_cselect_b64 s[14:15], -1, 0
	s_cmp_lt_i32 s83, 4
	s_cbranch_scc0 .LBB0_701

.LBB0_709:
	v_add_co_u32_e32 v24, vcc, 0x10000, v2
	s_nop 1
	v_addc_co_u32_e32 v25, vcc, 0, v3, vcc
	v_add_co_u32_e32 v52, vcc, 0x12000, v2
	s_nop 1
	v_addc_co_u32_e32 v53, vcc, 0, v3, vcc
	global_load_dwordx4 v[24:27], v[24:25], off
	s_nop 0
	global_load_dwordx4 v[52:55], v[52:53], off
	s_cmp_gt_i32 s83, 5
	s_cselect_b64 s[10:11], -1, 0
	s_cmp_lt_i32 s83, 6
	s_cbranch_scc0 .LBB0_703

.LBB0_711:
	v_add_co_u32_e32 v40, vcc, 0x18000, v2
	s_nop 1
	v_addc_co_u32_e32 v41, vcc, 0, v3, vcc
	v_add_co_u32_e32 v64, vcc, 0x1a000, v2
	s_nop 1
	v_addc_co_u32_e32 v65, vcc, 0, v3, vcc
	global_load_dwordx4 v[40:43], v[40:41], off
	s_nop 0
	global_load_dwordx4 v[64:67], v[64:65], off
	s_cmp_gt_i32 s83, 7
	s_cselect_b64 s[6:7], -1, 0
	s_cmp_lt_i32 s83, 8
	s_cbranch_scc0 .LBB0_705

.LBB0_713:
	v_add_co_u32_e32 v56, vcc, 0x20000, v2
	s_nop 1
	v_addc_co_u32_e32 v57, vcc, 0, v3, vcc
	v_add_co_u32_e32 v2, vcc, 0x22000, v2
	s_nop 1
	v_addc_co_u32_e32 v3, vcc, 0, v3, vcc
	global_load_dwordx4 v[56:59], v[56:57], off
	s_nop 0
	global_load_dwordx4 v[72:75], v[2:3], off

.LBB0_786:
	v_add_u32_e32 v1, s34, v226
	v_or_b32_e32 v2, 4, v1
	s_sub_i32 s27, s36, s35
	v_cmp_ge_i32_e64 s[34:35], v2, v237
	v_cmp_lt_i32_e64 s[36:37], v2, v238
	v_sub_u32_e32 v2, v2, v224
	v_max_i32_e32 v84, -15, v2
	v_sub_u32_e32 v2, v1, v224
	v_add_u32_e32 v84, 15, v84
	v_or_b32_e32 v86, 1, v1
	s_mulk_i32 s28, 0x744
	v_max_i32_e32 v2, -15, v2
	v_min_u32_e32 v90, 30, v84
	v_sub_u32_e32 v84, v86, v224
	s_add_i32 s26, s28, 0
	s_mulk_i32 s27, 0x7c
	v_add_u32_e32 v2, 15, v2
	v_max_i32_e32 v84, -15, v84
	s_add_i32 s44, s26, s27
	v_min_u32_e32 v2, 30, v2
	v_add_u32_e32 v84, 15, v84
	v_lshl_add_u32 v148, v2, 2, s44
	v_min_u32_e32 v84, 30, v84
	ds_read2_b32 v[2:3], v148 offset0:217 offset1:248
	v_lshl_add_u32 v149, v84, 2, s44
	ds_read2_b32 v[84:85], v149 offset0:217 offset1:248
	v_cmp_ge_i32_e32 vcc, v1, v237
	v_cmp_lt_i32_e64 s[26:27], v1, v238
	s_waitcnt lgkmcnt(1)
	v_fmamk_f32 v2, v144, 0x3db504f3, v2
	s_and_b64 vcc, vcc, s[26:27]
	v_cndmask_b32_e32 v150, v244, v2, vcc
	s_waitcnt lgkmcnt(0)
	v_fmamk_f32 v2, v145, 0x3db504f3, v84
	v_or_b32_e32 v84, 2, v1
	v_cmp_ge_i32_e64 s[26:27], v86, v237
	v_cmp_lt_i32_e64 s[28:29], v86, v238
	v_sub_u32_e32 v86, v84, v224
	v_max_i32_e32 v86, -15, v86
	v_add_u32_e32 v86, 15, v86
	v_min_u32_e32 v86, 30, v86
	v_lshl_add_u32 v151, v86, 2, s44
	ds_read2_b32 v[86:87], v151 offset0:217 offset1:248
	s_and_b64 s[26:27], s[26:27], s[28:29]
	v_cndmask_b32_e64 v152, v244, v2, s[26:27]
	s_mov_b32 s28, 0xff61b1e6
	v_max3_f32 v2, v150, s28, v152
	v_cmp_ge_i32_e64 s[28:29], v84, v237
	v_cmp_lt_i32_e64 s[30:31], v84, v238
	s_waitcnt lgkmcnt(0)
	v_fmamk_f32 v84, v146, 0x3db504f3, v86
	s_and_b64 s[28:29], s[28:29], s[30:31]
	v_cndmask_b32_e64 v153, v244, v84, s[28:29]
	v_or_b32_e32 v84, 3, v1
	v_sub_u32_e32 v86, v84, v224
	v_max_i32_e32 v86, -15, v86
	v_add_u32_e32 v86, 15, v86
	v_min_u32_e32 v86, 30, v86
	v_lshl_add_u32 v154, v86, 2, s44
	ds_read2_b32 v[88:89], v154 offset0:217 offset1:248
	v_or_b32_e32 v86, 5, v1
	v_cmp_ge_i32_e64 s[30:31], v84, v237
	v_cmp_lt_i32_e64 s[38:39], v84, v238
	v_lshl_add_u32 v155, v90, 2, s44
	s_waitcnt lgkmcnt(0)
	v_fmamk_f32 v84, v147, 0x3db504f3, v88
	v_sub_u32_e32 v88, v86, v224
	v_max_i32_e32 v88, -15, v88
	v_add_u32_e32 v88, 15, v88
	v_min_u32_e32 v88, 30, v88
	ds_read2_b32 v[90:91], v155 offset0:217 offset1:248
	v_lshl_add_u32 v157, v88, 2, s44
	s_and_b64 s[30:31], s[30:31], s[38:39]
	ds_read2_b32 v[144:145], v157 offset0:217 offset1:248
	s_and_b64 s[34:35], s[34:35], s[36:37]
	v_cmp_ge_i32_e64 s[36:37], v86, v237
	v_cmp_lt_i32_e64 s[38:39], v86, v238
	v_or_b32_e32 v86, 6, v1
	v_sub_u32_e32 v88, v86, v224
	v_max_i32_e32 v88, -15, v88
	v_add_u32_e32 v88, 15, v88
	v_cndmask_b32_e64 v156, v244, v84, s[30:31]
	s_waitcnt lgkmcnt(1)
	v_fmamk_f32 v84, v140, 0x3db504f3, v90
	v_min_u32_e32 v88, 30, v88
	v_cndmask_b32_e64 v158, v244, v84, s[34:35]
	s_waitcnt lgkmcnt(0)
	v_fmamk_f32 v84, v141, 0x3db504f3, v144
	v_lshl_add_u32 v144, v88, 2, s44
	ds_read2_b32 v[140:141], v144 offset0:217 offset1:248
	s_and_b64 s[36:37], s[36:37], s[38:39]
	v_cmp_ge_i32_e64 s[38:39], v86, v237
	v_cmp_lt_i32_e64 s[40:41], v86, v238
	v_or_b32_e32 v86, 7, v1
	v_sub_u32_e32 v88, v86, v224
	v_max_i32_e32 v88, -15, v88
	v_add_u32_e32 v88, 15, v88
	v_min_u32_e32 v88, 30, v88
	v_cndmask_b32_e64 v159, v244, v84, s[36:37]
	s_waitcnt lgkmcnt(0)
	v_fmamk_f32 v84, v142, 0x3db504f3, v140
	v_lshl_add_u32 v140, v88, 2, s44
	ds_read2_b32 v[146:147], v140 offset0:217 offset1:248
	s_and_b64 s[38:39], s[38:39], s[40:41]
	v_cmp_ge_i32_e64 s[40:41], v86, v237
	v_cmp_lt_i32_e64 s[44:45], v86, v238
	v_max3_f32 v2, v2, v153, v156
	v_cndmask_b32_e64 v142, v244, v84, s[38:39]
	s_waitcnt lgkmcnt(0)
	v_fmamk_f32 v84, v143, 0x3db504f3, v146
	s_and_b64 s[40:41], s[40:41], s[44:45]
	v_max3_f32 v2, v2, v158, v159
	v_cndmask_b32_e64 v143, v244, v84, s[40:41]
	v_fmac_f32_e32 v3, 0x3db504f3, v136
	v_fmac_f32_e32 v85, 0x3db504f3, v137
	v_max3_f32 v2, v2, v142, v143
	v_cndmask_b32_e32 v146, v244, v3, vcc
	v_cndmask_b32_e64 v160, v244, v85, s[26:27]
	v_fmac_f32_e32 v87, 0x3db504f3, v138
	v_fmac_f32_e32 v89, 0x3db504f3, v139
	v_max3_f32 v2, v2, v146, v160
	v_cndmask_b32_e64 v161, v244, v87, s[28:29]
	v_cndmask_b32_e64 v162, v244, v89, s[30:31]
	v_fmac_f32_e32 v91, 0x3db504f3, v132
	v_fmac_f32_e32 v145, 0x3db504f3, v133
	v_max3_f32 v2, v2, v161, v162
	v_cndmask_b32_e64 v163, v244, v91, s[34:35]
	v_cndmask_b32_e64 v145, v244, v145, s[36:37]
	v_add_u32_e32 v132, 0x400, v148
	v_max3_f32 v86, v2, v163, v145
	ds_read2_b32 v[2:3], v132 offset0:23 offset1:54
	v_add_u32_e32 v133, 0x400, v149
	ds_read2_b32 v[84:85], v133 offset0:23 offset1:54
	v_fmac_f32_e32 v141, 0x3db504f3, v134
	v_fmac_f32_e32 v147, 0x3db504f3, v135
	v_cndmask_b32_e64 v141, v244, v141, s[38:39]
	v_cndmask_b32_e64 v147, v244, v147, s[40:41]
	s_waitcnt lgkmcnt(1)
	v_fmamk_f32 v2, v128, 0x3db504f3, v2
	v_add_u32_e32 v134, 0x400, v151
	v_max3_f32 v90, v86, v141, v147
	v_cndmask_b32_e32 v148, v244, v2, vcc
	s_waitcnt lgkmcnt(0)
	v_fmamk_f32 v2, v129, 0x3db504f3, v84
	ds_read2_b32 v[86:87], v134 offset0:23 offset1:54
	v_add_u32_e32 v135, 0x400, v154
	ds_read2_b32 v[88:89], v135 offset0:23 offset1:54
	v_cndmask_b32_e64 v149, v244, v2, s[26:27]
	v_add_u32_e32 v136, 0x400, v155
	v_max3_f32 v2, v90, v148, v149
	ds_read2_b32 v[90:91], v136 offset0:23 offset1:54
	v_add_u32_e32 v137, 0x400, v157
	ds_read2_b32 v[128:129], v137 offset0:23 offset1:54
	s_waitcnt lgkmcnt(3)
	v_fmamk_f32 v84, v130, 0x3db504f3, v86
	v_cndmask_b32_e64 v151, v244, v84, s[28:29]
	s_waitcnt lgkmcnt(2)
	v_fmamk_f32 v84, v131, 0x3db504f3, v88
	v_cndmask_b32_e64 v154, v244, v84, s[30:31]
	s_waitcnt lgkmcnt(1)
	v_fmamk_f32 v84, v124, 0x3db504f3, v90
	v_cndmask_b32_e64 v155, v244, v84, s[34:35]
	s_waitcnt lgkmcnt(0)
	v_fmamk_f32 v84, v125, 0x3db504f3, v128
	v_add_u32_e32 v128, 0x400, v144
	ds_read2_b32 v[124:125], v128 offset0:23 offset1:54
	v_add_u32_e32 v138, 0x400, v140
	ds_read2_b32 v[130:131], v138 offset0:23 offset1:54
	v_cndmask_b32_e64 v140, v244, v84, s[36:37]
	v_max3_f32 v2, v2, v151, v154
	s_waitcnt lgkmcnt(1)
	v_fmamk_f32 v84, v126, 0x3db504f3, v124
	v_cndmask_b32_e64 v144, v244, v84, s[38:39]
	s_waitcnt lgkmcnt(0)
	v_fmamk_f32 v84, v127, 0x3db504f3, v130
	v_max3_f32 v2, v2, v155, v140
	v_cndmask_b32_e64 v157, v244, v84, s[40:41]
	v_fmac_f32_e32 v3, 0x3db504f3, v120
	v_fmac_f32_e32 v85, 0x3db504f3, v121
	v_max3_f32 v2, v2, v144, v157
	v_cndmask_b32_e32 v164, v244, v3, vcc
	v_cndmask_b32_e64 v165, v244, v85, s[26:27]
	v_fmac_f32_e32 v87, 0x3db504f3, v122
	v_fmac_f32_e32 v89, 0x3db504f3, v123
	v_max3_f32 v2, v2, v164, v165
	v_cndmask_b32_e64 v166, v244, v87, s[28:29]
	v_cndmask_b32_e64 v167, v244, v89, s[30:31]
	v_fmac_f32_e32 v91, 0x3db504f3, v116
	v_fmac_f32_e32 v129, 0x3db504f3, v117
	v_max3_f32 v2, v2, v166, v167
	v_cndmask_b32_e64 v168, v244, v91, s[34:35]
	v_cndmask_b32_e64 v169, v244, v129, s[36:37]
	v_max3_f32 v86, v2, v168, v169
	ds_read2_b32 v[2:3], v132 offset0:85 offset1:116
	ds_read2_b32 v[84:85], v133 offset0:85 offset1:116
	v_fmac_f32_e32 v125, 0x3db504f3, v118
	v_fmac_f32_e32 v131, 0x3db504f3, v119
	v_cndmask_b32_e64 v170, v244, v125, s[38:39]
	v_cndmask_b32_e64 v171, v244, v131, s[40:41]
	s_waitcnt lgkmcnt(1)
	v_fmamk_f32 v2, v112, 0x3db504f3, v2
	v_max3_f32 v90, v86, v170, v171
	v_cndmask_b32_e32 v172, v244, v2, vcc
	ds_read2_b32 v[86:87], v134 offset0:85 offset1:116
	s_waitcnt lgkmcnt(1)
	v_fmamk_f32 v2, v113, 0x3db504f3, v84
	v_cndmask_b32_e64 v173, v244, v2, s[26:27]
	ds_read2_b32 v[88:89], v135 offset0:85 offset1:116
	v_max3_f32 v2, v90, v172, v173
	ds_read2_b32 v[90:91], v136 offset0:85 offset1:116
	ds_read2_b32 v[112:113], v137 offset0:85 offset1:116
	s_waitcnt lgkmcnt(3)
	v_fmamk_f32 v84, v114, 0x3db504f3, v86
	v_cndmask_b32_e64 v174, v244, v84, s[28:29]
	s_waitcnt lgkmcnt(2)
	v_fmamk_f32 v84, v115, 0x3db504f3, v88
	v_cndmask_b32_e64 v175, v244, v84, s[30:31]
	s_waitcnt lgkmcnt(1)
	v_fmamk_f32 v84, v108, 0x3db504f3, v90
	ds_read2_b32 v[114:115], v128 offset0:85 offset1:116
	v_cndmask_b32_e64 v176, v244, v84, s[34:35]
	s_waitcnt lgkmcnt(1)
	v_fmamk_f32 v84, v109, 0x3db504f3, v112
	ds_read2_b32 v[108:109], v138 offset0:85 offset1:116
	v_cndmask_b32_e64 v177, v244, v84, s[36:37]
	s_waitcnt lgkmcnt(1)
	v_fmamk_f32 v84, v110, 0x3db504f3, v114
	v_max3_f32 v2, v2, v174, v175
	v_cndmask_b32_e64 v178, v244, v84, s[38:39]
	s_waitcnt lgkmcnt(0)
	v_fmamk_f32 v84, v111, 0x3db504f3, v108
	v_max3_f32 v2, v2, v176, v177
	v_cndmask_b32_e64 v179, v244, v84, s[40:41]
	v_fmac_f32_e32 v3, 0x3db504f3, v104
	v_fmac_f32_e32 v85, 0x3db504f3, v105
	v_max3_f32 v2, v2, v178, v179
	v_cndmask_b32_e32 v180, v244, v3, vcc
	v_cndmask_b32_e64 v181, v244, v85, s[26:27]
	v_fmac_f32_e32 v87, 0x3db504f3, v106
	v_fmac_f32_e32 v89, 0x3db504f3, v107
	v_max3_f32 v2, v2, v180, v181
	v_cndmask_b32_e64 v182, v244, v87, s[28:29]
	v_cndmask_b32_e64 v183, v244, v89, s[30:31]
	v_fmac_f32_e32 v91, 0x3db504f3, v100
	v_fmac_f32_e32 v113, 0x3db504f3, v101
	v_max3_f32 v2, v2, v182, v183
	v_cndmask_b32_e64 v184, v244, v91, s[34:35]
	v_cndmask_b32_e64 v185, v244, v113, s[36:37]
	v_max3_f32 v86, v2, v184, v185
	ds_read2_b32 v[2:3], v132 offset0:147 offset1:178
	ds_read2_b32 v[84:85], v133 offset0:147 offset1:178
	v_fmac_f32_e32 v115, 0x3db504f3, v102
	v_fmac_f32_e32 v109, 0x3db504f3, v103
	v_cndmask_b32_e64 v186, v244, v115, s[38:39]
	v_cndmask_b32_e64 v187, v244, v109, s[40:41]
	s_waitcnt lgkmcnt(1)
	v_fmamk_f32 v2, v96, 0x3db504f3, v2
	s_waitcnt lgkmcnt(0)
	v_fmamk_f32 v84, v97, 0x3db504f3, v84
	v_max3_f32 v90, v86, v186, v187
	v_cndmask_b32_e32 v2, v244, v2, vcc
	v_cndmask_b32_e64 v188, v244, v84, s[26:27]
	ds_read2_b32 v[86:87], v134 offset0:147 offset1:178
	ds_read2_b32 v[88:89], v135 offset0:147 offset1:178
	v_max3_f32 v84, v90, v2, v188
	ds_read2_b32 v[90:91], v136 offset0:147 offset1:178
	ds_read2_b32 v[96:97], v137 offset0:147 offset1:178
	s_waitcnt lgkmcnt(3)
	v_fmamk_f32 v86, v98, 0x3db504f3, v86
	s_waitcnt lgkmcnt(2)
	v_fmamk_f32 v88, v99, 0x3db504f3, v88
	ds_read2_b32 v[98:99], v128 offset0:147 offset1:178
	s_waitcnt lgkmcnt(2)
	v_fmamk_f32 v90, v92, 0x3db504f3, v90
	s_waitcnt lgkmcnt(1)
	v_fmamk_f32 v96, v93, 0x3db504f3, v96
	ds_read2_b32 v[92:93], v138 offset0:147 offset1:178
	v_cndmask_b32_e64 v86, v244, v86, s[28:29]
	v_cndmask_b32_e64 v88, v244, v88, s[30:31]
	v_max3_f32 v84, v84, v86, v88
	v_cndmask_b32_e64 v90, v244, v90, s[34:35]
	v_cndmask_b32_e64 v189, v244, v96, s[36:37]
	s_waitcnt lgkmcnt(1)
	v_fmamk_f32 v94, v94, 0x3db504f3, v98
	s_waitcnt lgkmcnt(0)
	v_fmamk_f32 v92, v95, 0x3db504f3, v92
	v_max3_f32 v84, v84, v90, v189
	v_cndmask_b32_e64 v190, v244, v94, s[38:39]
	v_cndmask_b32_e64 v191, v244, v92, s[40:41]
	v_fmac_f32_e32 v3, 0x3db504f3, v76
	v_fmac_f32_e32 v85, 0x3db504f3, v77
	v_max3_f32 v84, v84, v190, v191
	v_cndmask_b32_e32 v3, v244, v3, vcc
	v_cndmask_b32_e64 v77, v244, v85, s[26:27]
	v_fmac_f32_e32 v87, 0x3db504f3, v78
	v_fmac_f32_e32 v89, 0x3db504f3, v79
	v_and_b32_e32 v85, 64, v240
	v_max3_f32 v76, v84, v3, v77
	v_cndmask_b32_e64 v78, v244, v87, s[28:29]
	v_cndmask_b32_e64 v79, v244, v89, s[30:31]
	v_fmac_f32_e32 v91, 0x3db504f3, v80
	v_fmac_f32_e32 v97, 0x3db504f3, v81
	v_xor_b32_e32 v84, 16, v240
	v_add_u32_e32 v85, 64, v85
	v_max3_f32 v76, v76, v78, v79
	v_cndmask_b32_e64 v80, v244, v91, s[34:35]
	v_cndmask_b32_e64 v81, v244, v97, s[36:37]
	v_fmac_f32_e32 v99, 0x3db504f3, v82
	v_fmac_f32_e32 v93, 0x3db504f3, v83
	v_cmp_lt_i32_e32 vcc, v84, v85
	v_max3_f32 v76, v76, v80, v81
	v_cndmask_b32_e64 v82, v244, v99, s[38:39]
	v_cndmask_b32_e64 v83, v244, v93, s[40:41]
	v_cndmask_b32_e32 v84, v240, v84, vcc
	v_max3_f32 v76, v76, v82, v83
	v_lshlrev_b32_e32 v245, 2, v84
	ds_bpermute_b32 v84, v245, v76
	s_waitcnt vmcnt(0)
	ds_write_b128 v241, v[4:7] offset:15360
	ds_write_b128 v241, v[8:11] offset:24576
	s_waitcnt lgkmcnt(0)
	s_barrier
	s_waitcnt lgkmcnt(2)
	v_max_f32_e32 v84, v84, v84
	v_max_f32_e32 v76, v76, v84
	v_xor_b32_e32 v84, 32, v240
	v_cmp_lt_i32_e32 vcc, v84, v85
	v_lshl_add_u32 v249, v1, 1, v239
	s_nop 0
	v_cndmask_b32_e32 v84, v240, v84, vcc
	v_lshlrev_b32_e32 v246, 2, v84
	ds_bpermute_b32 v84, v246, v76
	s_and_b64 vcc, exec, s[24:25]
	s_waitcnt lgkmcnt(0)
	v_max_f32_e32 v84, v84, v84
	v_max_f32_e32 v192, v76, v84
	v_sub_f32_e32 v84, v158, v192
	v_mul_f32_e32 v84, 0x3fb8aa3b, v84
	v_exp_f32_e32 v136, v84
	v_sub_f32_e32 v84, v159, v192
	v_mul_f32_e32 v84, 0x3fb8aa3b, v84
	v_exp_f32_e32 v137, v84
	v_sub_f32_e32 v84, v142, v192
	v_mul_f32_e32 v84, 0x3fb8aa3b, v84
	v_exp_f32_e32 v138, v84
	v_sub_f32_e32 v84, v143, v192
	v_mul_f32_e32 v84, 0x3fb8aa3b, v84
	v_exp_f32_e32 v139, v84
	v_sub_f32_e32 v84, v146, v192
	v_mul_f32_e32 v84, 0x3fb8aa3b, v84
	v_exp_f32_e32 v124, v84
	v_sub_f32_e32 v84, v160, v192
	v_mul_f32_e32 v84, 0x3fb8aa3b, v84
	v_exp_f32_e32 v125, v84
	v_sub_f32_e32 v84, v161, v192
	v_mul_f32_e32 v84, 0x3fb8aa3b, v84
	v_exp_f32_e32 v126, v84
	v_sub_f32_e32 v84, v162, v192
	v_mul_f32_e32 v84, 0x3fb8aa3b, v84
	v_exp_f32_e32 v127, v84
	v_sub_f32_e32 v84, v163, v192
	v_mul_f32_e32 v84, 0x3fb8aa3b, v84
	v_exp_f32_e32 v128, v84
	v_sub_f32_e32 v84, v145, v192
	v_mul_f32_e32 v84, 0x3fb8aa3b, v84
	v_exp_f32_e32 v129, v84
	v_sub_f32_e32 v84, v141, v192
	v_mul_f32_e32 v84, 0x3fb8aa3b, v84
	v_exp_f32_e32 v130, v84
	v_sub_f32_e32 v84, v147, v192
	v_mul_f32_e32 v84, 0x3fb8aa3b, v84
	v_exp_f32_e32 v131, v84
	v_sub_f32_e32 v84, v148, v192
	v_mul_f32_e32 v84, 0x3fb8aa3b, v84
	v_exp_f32_e32 v116, v84
	v_sub_f32_e32 v84, v149, v192
	v_mul_f32_e32 v84, 0x3fb8aa3b, v84
	v_exp_f32_e32 v117, v84
	v_sub_f32_e32 v84, v151, v192
	v_mul_f32_e32 v84, 0x3fb8aa3b, v84
	v_exp_f32_e32 v118, v84
	v_sub_f32_e32 v84, v154, v192
	v_mul_f32_e32 v84, 0x3fb8aa3b, v84
	v_exp_f32_e32 v119, v84
	v_sub_f32_e32 v84, v155, v192
	v_mul_f32_e32 v84, 0x3fb8aa3b, v84
	v_exp_f32_e32 v120, v84
	v_sub_f32_e32 v84, v140, v192
	v_mul_f32_e32 v84, 0x3fb8aa3b, v84
	v_exp_f32_e32 v121, v84
	v_sub_f32_e32 v84, v144, v192
	v_sub_f32_e32 v76, v150, v192
	v_mul_f32_e32 v84, 0x3fb8aa3b, v84
	v_mul_f32_e32 v76, 0x3fb8aa3b, v76
	v_exp_f32_e32 v122, v84
	v_sub_f32_e32 v84, v157, v192
	v_exp_f32_e32 v132, v76
	v_sub_f32_e32 v76, v152, v192
	v_mul_f32_e32 v84, 0x3fb8aa3b, v84
	v_mul_f32_e32 v76, 0x3fb8aa3b, v76
	v_exp_f32_e32 v123, v84
	v_sub_f32_e32 v84, v164, v192
	v_exp_f32_e32 v133, v76
	v_sub_f32_e32 v76, v153, v192
	v_mul_f32_e32 v84, 0x3fb8aa3b, v84
	v_mul_f32_e32 v76, 0x3fb8aa3b, v76
	v_exp_f32_e32 v108, v84
	v_sub_f32_e32 v84, v165, v192
	v_exp_f32_e32 v134, v76
	v_sub_f32_e32 v76, v156, v192
	v_mul_f32_e32 v84, 0x3fb8aa3b, v84
	v_mul_f32_e32 v76, 0x3fb8aa3b, v76
	v_exp_f32_e32 v109, v84
	v_sub_f32_e32 v84, v166, v192
	v_exp_f32_e32 v135, v76
	v_mul_f32_e32 v84, 0x3fb8aa3b, v84
	v_add_f32_e32 v76, 0, v132
	v_exp_f32_e32 v110, v84
	v_sub_f32_e32 v84, v167, v192
	v_add_f32_e32 v76, v76, v133
	v_mul_f32_e32 v84, 0x3fb8aa3b, v84
	v_add_f32_e32 v76, v76, v134
	v_exp_f32_e32 v111, v84
	v_sub_f32_e32 v84, v168, v192
	v_add_f32_e32 v76, v76, v135
	v_mul_f32_e32 v84, 0x3fb8aa3b, v84
	v_add_f32_e32 v76, v76, v136
	v_exp_f32_e32 v112, v84
	v_sub_f32_e32 v84, v169, v192
	v_add_f32_e32 v76, v76, v137
	v_mul_f32_e32 v84, 0x3fb8aa3b, v84
	v_add_f32_e32 v76, v76, v138
	v_exp_f32_e32 v113, v84
	v_sub_f32_e32 v84, v170, v192
	v_add_f32_e32 v76, v76, v139
	v_mul_f32_e32 v84, 0x3fb8aa3b, v84
	v_add_f32_e32 v76, v76, v124
	v_exp_f32_e32 v114, v84
	v_sub_f32_e32 v84, v171, v192
	v_add_f32_e32 v76, v76, v125
	v_mul_f32_e32 v84, 0x3fb8aa3b, v84
	v_add_f32_e32 v76, v76, v126
	v_exp_f32_e32 v115, v84
	v_sub_f32_e32 v84, v172, v192
	v_add_f32_e32 v76, v76, v127
	v_mul_f32_e32 v84, 0x3fb8aa3b, v84
	v_add_f32_e32 v76, v76, v128
	v_exp_f32_e32 v100, v84
	v_sub_f32_e32 v84, v173, v192
	v_add_f32_e32 v76, v76, v129
	v_mul_f32_e32 v84, 0x3fb8aa3b, v84
	v_add_f32_e32 v76, v76, v130
	v_exp_f32_e32 v101, v84
	v_sub_f32_e32 v84, v174, v192
	v_add_f32_e32 v76, v76, v131
	v_mul_f32_e32 v84, 0x3fb8aa3b, v84
	v_add_f32_e32 v76, v76, v116
	v_exp_f32_e32 v102, v84
	v_sub_f32_e32 v84, v175, v192
	v_add_f32_e32 v76, v76, v117
	v_mul_f32_e32 v84, 0x3fb8aa3b, v84
	v_add_f32_e32 v76, v76, v118
	v_exp_f32_e32 v103, v84
	v_sub_f32_e32 v84, v176, v192
	v_add_f32_e32 v76, v76, v119
	v_mul_f32_e32 v84, 0x3fb8aa3b, v84
	v_add_f32_e32 v76, v76, v120
	v_exp_f32_e32 v104, v84
	v_sub_f32_e32 v84, v177, v192
	v_add_f32_e32 v76, v76, v121
	v_mul_f32_e32 v84, 0x3fb8aa3b, v84
	v_add_f32_e32 v76, v76, v122
	v_exp_f32_e32 v105, v84
	v_sub_f32_e32 v84, v178, v192
	v_add_f32_e32 v76, v76, v123
	v_mul_f32_e32 v84, 0x3fb8aa3b, v84
	v_add_f32_e32 v76, v76, v108
	v_exp_f32_e32 v106, v84
	v_sub_f32_e32 v84, v179, v192
	v_add_f32_e32 v76, v76, v109
	v_mul_f32_e32 v84, 0x3fb8aa3b, v84
	v_add_f32_e32 v76, v76, v110
	v_exp_f32_e32 v107, v84
	v_sub_f32_e32 v84, v180, v192
	v_add_f32_e32 v76, v76, v111
	v_mul_f32_e32 v84, 0x3fb8aa3b, v84
	v_add_f32_e32 v76, v76, v112
	v_exp_f32_e32 v92, v84
	v_sub_f32_e32 v84, v181, v192
	v_add_f32_e32 v76, v76, v113
	v_mul_f32_e32 v84, 0x3fb8aa3b, v84
	v_add_f32_e32 v76, v76, v114
	v_exp_f32_e32 v93, v84
	v_sub_f32_e32 v84, v182, v192
	v_add_f32_e32 v76, v76, v115
	v_mul_f32_e32 v84, 0x3fb8aa3b, v84
	v_add_f32_e32 v76, v76, v100
	v_exp_f32_e32 v94, v84
	v_sub_f32_e32 v84, v183, v192
	v_add_f32_e32 v76, v76, v101
	v_mul_f32_e32 v84, 0x3fb8aa3b, v84
	v_add_f32_e32 v76, v76, v102
	v_exp_f32_e32 v95, v84
	v_sub_f32_e32 v84, v184, v192
	v_add_f32_e32 v76, v76, v103
	v_mul_f32_e32 v84, 0x3fb8aa3b, v84
	v_add_f32_e32 v76, v76, v104
	v_exp_f32_e32 v96, v84
	v_sub_f32_e32 v84, v185, v192
	v_add_f32_e32 v76, v76, v105
	v_mul_f32_e32 v84, 0x3fb8aa3b, v84
	v_add_f32_e32 v76, v76, v106
	v_exp_f32_e32 v97, v84
	v_sub_f32_e32 v84, v186, v192
	v_add_f32_e32 v76, v76, v107
	v_mul_f32_e32 v84, 0x3fb8aa3b, v84
	v_add_f32_e32 v76, v76, v92
	v_exp_f32_e32 v98, v84
	v_sub_f32_e32 v84, v187, v192
	v_sub_f32_e32 v2, v2, v192
	v_add_f32_e32 v76, v76, v93
	v_mul_f32_e32 v84, 0x3fb8aa3b, v84
	v_mul_f32_e32 v2, 0x3fb8aa3b, v2
	v_add_f32_e32 v76, v76, v94
	v_exp_f32_e32 v99, v84
	v_exp_f32_e32 v84, v2
	v_sub_f32_e32 v2, v188, v192
	v_add_f32_e32 v76, v76, v95
	v_mul_f32_e32 v2, 0x3fb8aa3b, v2
	v_add_f32_e32 v76, v76, v96
	v_exp_f32_e32 v85, v2
	v_sub_f32_e32 v2, v86, v192
	v_add_f32_e32 v76, v76, v97
	v_mul_f32_e32 v2, 0x3fb8aa3b, v2
	v_add_f32_e32 v76, v76, v98
	v_exp_f32_e32 v86, v2
	v_sub_f32_e32 v2, v88, v192
	v_add_f32_e32 v76, v76, v99
	v_mul_f32_e32 v2, 0x3fb8aa3b, v2
	v_exp_f32_e32 v87, v2
	v_add_f32_e32 v2, v76, v84
	v_sub_f32_e32 v76, v90, v192
	v_mul_f32_e32 v76, 0x3fb8aa3b, v76
	v_exp_f32_e32 v88, v76
	v_sub_f32_e32 v76, v189, v192
	v_mul_f32_e32 v76, 0x3fb8aa3b, v76
	v_exp_f32_e32 v89, v76
	v_sub_f32_e32 v76, v190, v192
	v_mul_f32_e32 v76, 0x3fb8aa3b, v76
	v_exp_f32_e32 v90, v76
	v_sub_f32_e32 v76, v191, v192
	v_sub_f32_e32 v3, v3, v192
	v_mul_f32_e32 v76, 0x3fb8aa3b, v76
	v_mul_f32_e32 v3, 0x3fb8aa3b, v3
	v_exp_f32_e32 v91, v76
	v_exp_f32_e32 v76, v3
	v_sub_f32_e32 v3, v77, v192
	v_mul_f32_e32 v3, 0x3fb8aa3b, v3
	v_exp_f32_e32 v77, v3
	v_sub_f32_e32 v3, v78, v192
	v_mul_f32_e32 v3, 0x3fb8aa3b, v3
	v_add_f32_e32 v2, v2, v85
	v_exp_f32_e32 v78, v3
	v_sub_f32_e32 v3, v79, v192
	v_add_f32_e32 v2, v2, v86
	v_mul_f32_e32 v3, 0x3fb8aa3b, v3
	v_add_f32_e32 v2, v2, v87
	v_exp_f32_e32 v79, v3
	v_sub_f32_e32 v3, v80, v192
	v_add_f32_e32 v2, v2, v88
	v_mul_f32_e32 v3, 0x3fb8aa3b, v3
	v_add_f32_e32 v2, v2, v89
	v_exp_f32_e32 v80, v3
	v_sub_f32_e32 v3, v81, v192
	v_add_f32_e32 v2, v2, v90
	v_mul_f32_e32 v3, 0x3fb8aa3b, v3
	v_add_f32_e32 v2, v2, v91
	v_exp_f32_e32 v81, v3
	v_sub_f32_e32 v3, v82, v192
	v_add_f32_e32 v2, v2, v76
	v_mul_f32_e32 v3, 0x3fb8aa3b, v3
	v_add_f32_e32 v2, v2, v77
	v_exp_f32_e32 v82, v3
	v_sub_f32_e32 v3, v83, v192
	v_add_f32_e32 v2, v2, v78
	v_mul_f32_e32 v3, 0x3fb8aa3b, v3
	v_add_f32_e32 v2, v2, v79
	v_exp_f32_e32 v83, v3
	v_add_f32_e32 v2, v2, v80
	v_add_f32_e32 v2, v2, v81
	v_add_f32_e32 v2, v2, v82
	v_add_f32_e32 v2, v2, v83
	ds_bpermute_b32 v3, v245, v2
	s_waitcnt lgkmcnt(0)
	v_add_f32_e32 v247, v2, v3
	ds_bpermute_b32 v248, v246, v247
	s_cbranch_vccnz .LBB0_803
	s_and_b64 vcc, exec, s[22:23]
	s_cbranch_vccnz .LBB0_811
	v_add_u32_e32 v1, 0, v249
	v_cvt_pk_bf16_f32 v140, v132, v133
	v_cvt_pk_bf16_f32 v141, v134, v135
	v_cvt_pk_bf16_f32 v142, v136, v137
	v_cvt_pk_bf16_f32 v143, v138, v139
	ds_read_b128 v[144:147], v1 offset:15360
	ds_read_b128 v[148:151], v1 offset:17664
	s_waitcnt lgkmcnt(1)
	v_mfma_f32_16x16x32_bf16 v[200:203], v[144:147], v[140:143], 0
	ds_read_b128 v[144:147], v1 offset:19968
	s_waitcnt lgkmcnt(1)
	v_mfma_f32_16x16x32_bf16 v[192:195], v[148:151], v[140:143], 0
	ds_read_b128 v[148:151], v1 offset:22272
	s_waitcnt lgkmcnt(1)
	v_mfma_f32_16x16x32_bf16 v[184:187], v[144:147], v[140:143], 0
	ds_read_b128 v[144:147], v1 offset:24576
	s_waitcnt lgkmcnt(1)
	v_mfma_f32_16x16x32_bf16 v[176:179], v[148:151], v[140:143], 0
	ds_read_b128 v[148:151], v1 offset:26880
	s_waitcnt lgkmcnt(1)
	v_mfma_f32_16x16x32_bf16 v[168:171], v[144:147], v[140:143], 0
	ds_read_b128 v[144:147], v1 offset:29184
	s_waitcnt lgkmcnt(1)
	v_mfma_f32_16x16x32_bf16 v[160:163], v[148:151], v[140:143], 0
	ds_read_b128 v[148:151], v1 offset:31488
	s_waitcnt lgkmcnt(1)
	v_mfma_f32_16x16x32_bf16 v[152:155], v[144:147], v[140:143], 0
	s_waitcnt lgkmcnt(0)
	v_mfma_f32_16x16x32_bf16 v[144:147], v[148:151], v[140:143], 0
	s_and_b64 vcc, exec, s[20:21]
	s_cbranch_vccz .LBB0_812
	s_branch .LBB0_813
